# baseline (speedup 1.0000x reference)
.LBB0_193:
	s_nop 7
	v_max_f32_e32 v34, v17, v17
	v_max_f32_e32 v35, v16, v16
	v_max_f32_e32 v34, v35, v34
	v_max3_f32 v34, v34, v18, v19
	v_max3_f32 v34, v34, v20, v21
	v_max3_f32 v34, v34, v22, v23
	v_max3_f32 v34, v34, v24, v25
	v_max3_f32 v34, v34, v26, v27
	v_max3_f32 v34, v34, v28, v29
	v_max3_f32 v34, v34, v30, v31
	v_max3_f32 v34, v34, v0, v1
	v_max3_f32 v34, v34, v2, v3
	v_max3_f32 v34, v34, v4, v5
	v_max3_f32 v34, v34, v6, v7
	v_max3_f32 v34, v34, v8, v9
	v_max3_f32 v34, v34, v10, v11
	v_max3_f32 v34, v34, v12, v13
	v_max3_f32 v34, v34, v14, v15
	v_mov_b32_e32 v35, v34
	s_nop 1
	v_permlane32_swap_b32_e32 v34, v35
	v_max_f32_e32 v35, v35, v35
	v_max_f32_e32 v34, v34, v34
	v_max_f32_e32 v34, v34, v35
	v_add_f32_e32 v35, 0x7149f2ca, v34
	v_mul_f32_e32 v35, 0x3e000000, v35
	s_mov_b32 s8, 0x41800000
	v_cmp_ge_f32_e32 vcc, s8, v35
	s_cmp_eq_u64 vcc, exec
	s_cselect_b64 vcc, -1, 0
	v_cmp_lt_i32_e64 s[8:9], 3, v32
	s_and_saveexec_b64 s[10:11], s[8:9]
	s_cbranch_execz .Lat_noprio
	s_setprio 1
.Lat_noprio:
	s_or_b64 exec, exec, s[10:11]
	v_max_f32_e32 v34, 0xf149f2ca, v34
	v_mov_b32_e32 v32, 0xf149f2ca
	v_cndmask_b32_e32 v163, v34, v32, vcc
	v_mul_f32_e32 v32, 0xbe38aa3b, v163
	v_fmamk_f32 v16, v16, 0x3e38aa3b, v32
	v_exp_f32_e32 v188, v16
	v_sub_f32_e32 v16, 0xf149f2ca, v34
	v_mul_f32_e32 v16, 0x3e38aa3b, v16
	v_fmamk_f32 v17, v17, 0x3e38aa3b, v32
	v_fmamk_f32 v18, v18, 0x3e38aa3b, v32
	v_fmamk_f32 v19, v19, 0x3e38aa3b, v32
	v_fmamk_f32 v20, v20, 0x3e38aa3b, v32
	v_fmamk_f32 v21, v21, 0x3e38aa3b, v32
	v_fmamk_f32 v22, v22, 0x3e38aa3b, v32
	v_fmamk_f32 v23, v23, 0x3e38aa3b, v32
	v_fmamk_f32 v24, v24, 0x3e38aa3b, v32
	v_fmamk_f32 v25, v25, 0x3e38aa3b, v32
	v_fmamk_f32 v26, v26, 0x3e38aa3b, v32
	v_fmamk_f32 v27, v27, 0x3e38aa3b, v32
	v_fmamk_f32 v28, v28, 0x3e38aa3b, v32
	v_fmamk_f32 v29, v29, 0x3e38aa3b, v32
	v_fmamk_f32 v30, v30, 0x3e38aa3b, v32
	v_fmamk_f32 v31, v31, 0x3e38aa3b, v32
	v_exp_f32_e32 v16, v16
	v_exp_f32_e32 v190, v17
	v_exp_f32_e32 v186, v18
	v_exp_f32_e32 v189, v19
	v_exp_f32_e32 v184, v20
	v_exp_f32_e32 v187, v21
	v_exp_f32_e32 v183, v22
	v_exp_f32_e32 v185, v23
	v_exp_f32_e32 v171, v24
	v_exp_f32_e32 v180, v25
	v_exp_f32_e32 v170, v26
	v_exp_f32_e32 v172, v27
	v_exp_f32_e32 v169, v28
	v_exp_f32_e32 v182, v29
	v_exp_f32_e32 v173, v30
	v_exp_f32_e32 v181, v31
	v_pk_fma_f32 v[138:139], v[2:3], s[82:83], v[32:33] op_sel_hi:[1,0,0]
	v_pk_fma_f32 v[140:141], v[0:1], s[82:83], v[32:33] op_sel_hi:[1,0,0]
	v_and_b32_e32 v0, 0x3fffffc0, v143
	v_lshlrev_b32_e32 v2, 6, v143
	v_lshlrev_b32_e32 v0, 2, v0
	v_and_b32_e32 v1, 0x78, v33
	v_and_b32_e32 v2, 0x400, v2
	v_lshlrev_b32_e32 v3, 8, v146
	s_add_i32 s8, s3, 2
	v_cndmask_b32_e64 v149, v16, 1.0, vcc
	v_pk_fma_f32 v[86:87], v[14:15], s[82:83], v[32:33] op_sel_hi:[1,0,0]
	v_pk_fma_f32 v[88:89], v[12:13], s[82:83], v[32:33] op_sel_hi:[1,0,0]
	v_pk_fma_f32 v[90:91], v[10:11], s[82:83], v[32:33] op_sel_hi:[1,0,0]
	v_pk_fma_f32 v[94:95], v[8:9], s[82:83], v[32:33] op_sel_hi:[1,0,0]
	v_pk_fma_f32 v[134:135], v[6:7], s[82:83], v[32:33] op_sel_hi:[1,0,0]
	v_pk_fma_f32 v[136:137], v[4:5], s[82:83], v[32:33] op_sel_hi:[1,0,0]
	v_or3_b32 v151, v1, v2, v3
	s_cmp_ge_i32 s8, s77
	v_cmp_gt_u32_e64 s[8:9], 32, v144
	v_lshl_add_u32 v147, v148, 2, v0
	v_lshl_add_u32 v145, v157, 2, v0
	s_cbranch_scc1 .LBB0_221
	v_mov_b32_e32 v150, 0
	s_mov_b64 s[92:93], s[14:15]
	s_mov_b64 s[14:15], s[12:13]
	s_mov_b32 s12, s71
	s_mov_b32 s71, s46
	s_mov_b32 s70, s37
	s_mov_b32 s10, 2
	v_subrev_u32_e32 v128, s2, v157
	s_mov_b32 s2, 0
	s_sub_i32 s18, 0, s77
	s_add_i32 s19, s3, 3
	s_mov_b32 s86, 1
	v_mov_b32_e32 v166, v144
	v_mov_b32_e32 v16, 0
	v_mov_b32_e32 v17, v150
	v_mov_b32_e32 v18, v150
	v_mov_b32_e32 v19, v150
	v_mov_b32_e32 v20, v150
	v_mov_b32_e32 v21, v150
	v_mov_b32_e32 v22, v150
	v_mov_b32_e32 v23, v150
	v_mov_b32_e32 v24, v150
	v_mov_b32_e32 v25, v150
	v_mov_b32_e32 v26, v150
	v_mov_b32_e32 v27, v150
	v_mov_b32_e32 v28, v150
	v_mov_b32_e32 v29, v150
	v_mov_b32_e32 v30, v150
	v_mov_b32_e32 v31, v150
	v_mov_b32_e32 v0, 0
	v_mov_b32_e32 v1, v150
	v_mov_b32_e32 v2, v150
	v_mov_b32_e32 v3, v150
	v_mov_b32_e32 v4, v150
	v_mov_b32_e32 v5, v150
	v_mov_b32_e32 v6, v150
	v_mov_b32_e32 v7, v150
	v_mov_b32_e32 v8, v150
	v_mov_b32_e32 v9, v150
	v_mov_b32_e32 v10, v150
	v_mov_b32_e32 v11, v150
	v_mov_b32_e32 v12, v150
	v_mov_b32_e32 v13, v150
	v_mov_b32_e32 v14, v150
	v_mov_b32_e32 v15, v150
